# v42 plus the same sub/exp batch-of-4 regrouping in the two dilated-attention bodies (temps v248-251); bit-identical
# speedup vs baseline: 1.0076x; 1.0025x over previous
; #define LAS __attribute__((address_space(3)))
; __device__ __forceinline__ s16x4 vtr(const LAS unsigned char* p) { return __builtin_bit_cast(s16x4, __builtin_amdgcn_ds_read_tr16_b64_v4i16((LAS s16x4*)p)); }
; #define ATT_PACK(src, kk) do { _Pragma("unroll") for (int s2 = 0; s2 < 2; ++s2) { u32x4 w_; w_.x = cvt_pk_bf16(src[8 * s2], src[8 * s2 + 1]); w_.y = cvt_pk_bf16(src[8 * s2 + 2], src[8 * s2 + 3]); \
;             w_.z = cvt_pk_bf16(src[8 * s2 + 4], src[8 * s2 + 5]); w_.w = cvt_pk_bf16(src[8 * s2 + 6], src[8 * s2 + 7]); pf[kk][s2] = __builtin_bit_cast(bf16x8, w_); } } while (0)
; template <int MODE>
; __device__ __forceinline__ void att_smpv(f32x16 (&s)[2], f32x16 (&o)[4], float& mrun, float& lrun, float& Rrun, int tq, int tqmin, int tok0, int st, int dil, int h, int lane, const LAS unsigned char* vb) {
;     ...
;         f32x2 ps2 = (f32x2){0.f, 0.f};
; #pragma unroll
;         for (int kk = 0; kk < 2; ++kk)
; #pragma unroll
;             for (int e = 0; e < 16; e += 2) { const float p0 = __builtin_amdgcn_exp2f(s[kk][e] - mrun), p1 = __builtin_amdgcn_exp2f(s[kk][e + 1] - mrun); s[kk][e] = p0; s[kk][e + 1] = p1; ps2 += (f32x2){p0, p1}; }
;         lrun += ps2.x + ps2.y;
;         ATT_PACK(s[0], 0); ATT_PACK(s[1], 1);
;     ...
;     const int li = lane & 15, tq_ = li >> 2, tp = li & 3;
;     const unsigned base0 = (unsigned)((4 * h + tq_) * 256 + (tq_ << 6) + (2 * ((lane >> 4) & 1) + (tp >> 1)) * 16 + 8 * (tp & 1));
; #pragma unroll
;     for (int b = 0; b < 4; ++b)
; #pragma unroll
;         for (int kk = 0; kk < 2; ++kk)
; #pragma unroll
;             for (int s2 = 0; s2 < 2; ++s2) { const LAS unsigned char* p = vb + ((base0 ^ (unsigned)(b << 6)) + (unsigned)((32 * kk + 16 * s2) * 256));
;                 const s16x4 lo = vtr(p), hi = vtr(p + 8 * 256);
;                 const bf16x8 vf = (bf16x8){lo[0], lo[1], lo[2], lo[3], hi[0], hi[1], hi[2], hi[3]};
;                 o[b] = __builtin_amdgcn_mfma_f32_32x32x16_bf16(vf, pf[kk][s2], o[b], 0, 0, 0); }
.LBB0_296:
	v_sub_f32_e32 v248, v0, v177
	v_sub_f32_e32 v249, v83, v177
	v_sub_f32_e32 v250, v82, v177
	v_sub_f32_e32 v251, v85, v177
	v_exp_f32_e32 v80, v248
	v_exp_f32_e32 v81, v249
	v_exp_f32_e32 v82, v250
	v_exp_f32_e32 v83, v251
	v_sub_f32_e32 v248, v84, v177
	v_sub_f32_e32 v249, v87, v177
	v_sub_f32_e32 v250, v86, v177
	v_sub_f32_e32 v251, v89, v177
	v_exp_f32_e32 v84, v248
	v_exp_f32_e32 v85, v249
	v_exp_f32_e32 v86, v250
	v_exp_f32_e32 v87, v251
	v_sub_f32_e32 v248, v88, v177
	v_sub_f32_e32 v249, v91, v177
	v_sub_f32_e32 v250, v90, v177
	v_sub_f32_e32 v251, v93, v177
	v_exp_f32_e32 v88, v248
	v_exp_f32_e32 v89, v249
	v_exp_f32_e32 v90, v250
	v_exp_f32_e32 v91, v251
	v_sub_f32_e32 v248, v92, v177
	v_sub_f32_e32 v249, v95, v177
	v_sub_f32_e32 v250, v94, v177
	v_sub_f32_e32 v251, v96, v177
	v_exp_f32_e32 v92, v248
	v_exp_f32_e32 v93, v249
	v_exp_f32_e32 v94, v250
	v_exp_f32_e32 v95, v251
	v_sub_f32_e32 v248, v66, v177
	v_sub_f32_e32 v249, v97, v177
	v_exp_f32_e32 v96, v248
	v_exp_f32_e32 v97, v249
	v_sub_f32_e32 v0, v67, v177
	v_pk_add_f32 v[180:181], v[80:81], 0 op_sel_hi:[1,0]
	v_exp_f32_e32 v66, v0
	v_sub_f32_e32 v0, v178, v177
	v_pk_add_f32 v[180:181], v[82:83], v[180:181]
	v_exp_f32_e32 v67, v0
	v_sub_f32_e32 v0, v68, v177
	v_pk_add_f32 v[180:181], v[84:85], v[180:181]
	v_exp_f32_e32 v178, v0
	v_sub_f32_e32 v0, v179, v177
	v_pk_add_f32 v[180:181], v[86:87], v[180:181]
	v_exp_f32_e32 v179, v0
	v_sub_f32_e32 v0, v69, v177
	v_pk_add_f32 v[180:181], v[88:89], v[180:181]
	v_exp_f32_e32 v68, v0
	v_sub_f32_e32 v0, v73, v177
	v_pk_add_f32 v[180:181], v[90:91], v[180:181]
	v_exp_f32_e32 v69, v0
	v_sub_f32_e32 v0, v70, v177
	v_pk_add_f32 v[180:181], v[92:93], v[180:181]
	v_exp_f32_e32 v182, v0
	v_sub_f32_e32 v0, v75, v177
	v_pk_add_f32 v[180:181], v[94:95], v[180:181]
	v_exp_f32_e32 v183, v0
	v_sub_f32_e32 v0, v71, v177
	v_pk_add_f32 v[180:181], v[96:97], v[180:181]
	v_exp_f32_e32 v184, v0
	v_sub_f32_e32 v0, v76, v177
	v_pk_add_f32 v[180:181], v[66:67], v[180:181]
	v_exp_f32_e32 v185, v0
	v_pk_add_f32 v[180:181], v[178:179], v[180:181]
	v_sub_f32_e32 v0, v72, v177
	v_pk_add_f32 v[180:181], v[68:69], v[180:181]
	s_nop 0
	v_pk_add_f32 v[180:181], v[182:183], v[180:181]
	s_nop 0
	v_pk_add_f32 v[70:71], v[184:185], v[180:181]
	v_exp_f32_e32 v180, v0
	v_sub_f32_e32 v248, v77, v177
	v_sub_f32_e32 v249, v74, v177
	v_sub_f32_e32 v250, v78, v177
	v_exp_f32_e32 v181, v248
	v_exp_f32_e32 v186, v249
	v_exp_f32_e32 v187, v250
	v_pk_add_f32 v[70:71], v[180:181], v[70:71]
	s_nop 0
	v_pk_add_f32 v[70:71], v[186:187], v[70:71]
	s_nop 0
	v_add_f32_e32 v0, v70, v71
	v_add_f32_e32 v176, v176, v0
	v_add_u32_e32 v0, s48, v166
	v_cvt_pk_bf16_f32 v70, v80, v81
	v_cvt_pk_bf16_f32 v71, v82, v83
	v_cvt_pk_bf16_f32 v72, v84, v85
	v_cvt_pk_bf16_f32 v73, v86, v87
	v_cvt_pk_bf16_f32 v74, v88, v89
	v_cvt_pk_bf16_f32 v75, v90, v91
	v_cvt_pk_bf16_f32 v76, v92, v93
	v_cvt_pk_bf16_f32 v77, v94, v95
	v_cvt_pk_bf16_f32 v78, v96, v97
	v_cvt_pk_bf16_f32 v79, v66, v67
	v_cvt_pk_bf16_f32 v80, v178, v179
	v_cvt_pk_bf16_f32 v81, v68, v69
	v_cvt_pk_bf16_f32 v66, v182, v183
	v_cvt_pk_bf16_f32 v67, v184, v185
	v_cvt_pk_bf16_f32 v68, v180, v181
	v_cvt_pk_bf16_f32 v69, v186, v187
	s_waitcnt vmcnt(0)
	ds_read_b64_tr_b16 v[228:229], v0 offset:16384
	ds_read_b64_tr_b16 v[230:231], v0 offset:18432
	ds_read_b64_tr_b16 v[232:233], v0 offset:20480
	ds_read_b64_tr_b16 v[234:235], v0 offset:22528
	ds_read_b64_tr_b16 v[236:237], v0 offset:24576
	ds_read_b64_tr_b16 v[238:239], v0 offset:26624
	ds_read_b64_tr_b16 v[240:241], v0 offset:28672
	ds_read_b64_tr_b16 v[242:243], v0 offset:30720
	s_waitcnt lgkmcnt(6)
	v_mfma_f32_32x32x16_bf16 v[50:65], v[228:231], v[70:73], v[50:65]
	v_add_u32_e32 v0, s48, v167
	ds_read_b64_tr_b16 v[228:229], v0 offset:16384
	ds_read_b64_tr_b16 v[230:231], v0 offset:18432
	s_waitcnt lgkmcnt(6)
	v_mfma_f32_32x32x16_bf16 v[50:65], v[232:235], v[74:77], v[50:65]
	ds_read_b64_tr_b16 v[232:233], v0 offset:20480
	ds_read_b64_tr_b16 v[234:235], v0 offset:22528
	s_waitcnt lgkmcnt(6)
	v_mfma_f32_32x32x16_bf16 v[50:65], v[236:239], v[78:81], v[50:65]
	ds_read_b64_tr_b16 v[236:237], v0 offset:24576
	ds_read_b64_tr_b16 v[238:239], v0 offset:26624
	s_waitcnt lgkmcnt(6)
	v_mfma_f32_32x32x16_bf16 v[50:65], v[240:243], v[66:69], v[50:65]
	ds_read_b64_tr_b16 v[240:241], v0 offset:28672
	ds_read_b64_tr_b16 v[242:243], v0 offset:30720
	s_waitcnt lgkmcnt(6)
	v_mfma_f32_32x32x16_bf16 v[34:49], v[228:231], v[70:73], v[34:49]
	v_add_u32_e32 v0, s48, v168
	ds_read_b64_tr_b16 v[228:229], v0 offset:16384
	ds_read_b64_tr_b16 v[230:231], v0 offset:18432
	s_waitcnt lgkmcnt(6)
	v_mfma_f32_32x32x16_bf16 v[34:49], v[232:235], v[74:77], v[34:49]
	ds_read_b64_tr_b16 v[232:233], v0 offset:20480
	ds_read_b64_tr_b16 v[234:235], v0 offset:22528
	s_waitcnt lgkmcnt(6)
	v_mfma_f32_32x32x16_bf16 v[34:49], v[236:239], v[78:81], v[34:49]
	ds_read_b64_tr_b16 v[236:237], v0 offset:24576
	ds_read_b64_tr_b16 v[238:239], v0 offset:26624
	s_waitcnt lgkmcnt(6)
	v_mfma_f32_32x32x16_bf16 v[34:49], v[240:243], v[66:69], v[34:49]
	ds_read_b64_tr_b16 v[240:241], v0 offset:28672
	ds_read_b64_tr_b16 v[242:243], v0 offset:30720
	s_waitcnt lgkmcnt(6)
	v_mfma_f32_32x32x16_bf16 v[18:33], v[228:231], v[70:73], v[18:33]
	v_add_u32_e32 v0, s48, v169
	ds_read_b64_tr_b16 v[228:229], v0 offset:16384
	ds_read_b64_tr_b16 v[230:231], v0 offset:18432
	s_waitcnt lgkmcnt(6)
	v_mfma_f32_32x32x16_bf16 v[18:33], v[232:235], v[74:77], v[18:33]
	ds_read_b64_tr_b16 v[232:233], v0 offset:20480
	ds_read_b64_tr_b16 v[234:235], v0 offset:22528
	s_waitcnt lgkmcnt(6)
	v_mfma_f32_32x32x16_bf16 v[18:33], v[236:239], v[78:81], v[18:33]
	ds_read_b64_tr_b16 v[236:237], v0 offset:24576
	ds_read_b64_tr_b16 v[238:239], v0 offset:26624
	s_waitcnt lgkmcnt(6)
	v_mfma_f32_32x32x16_bf16 v[18:33], v[240:243], v[66:69], v[18:33]
	ds_read_b64_tr_b16 v[240:241], v0 offset:28672
	ds_read_b64_tr_b16 v[242:243], v0 offset:30720
	s_waitcnt lgkmcnt(6)
	v_mfma_f32_32x32x16_bf16 v[2:17], v[228:231], v[70:73], v[2:17]
	s_waitcnt lgkmcnt(4)
	v_mfma_f32_32x32x16_bf16 v[2:17], v[232:235], v[74:77], v[2:17]
	s_waitcnt lgkmcnt(2)
	v_mfma_f32_32x32x16_bf16 v[2:17], v[236:239], v[78:81], v[2:17]
	s_waitcnt lgkmcnt(0)
	v_mfma_f32_32x32x16_bf16 v[2:17], v[240:243], v[66:69], v[2:17]

; #define LAS __attribute__((address_space(3)))
; __device__ __forceinline__ s16x4 vtr(const LAS unsigned char* p) { return __builtin_bit_cast(s16x4, __builtin_amdgcn_ds_read_tr16_b64_v4i16((LAS s16x4*)p)); }
; #define ATT_PACK(src, kk) do { _Pragma("unroll") for (int s2 = 0; s2 < 2; ++s2) { u32x4 w_; w_.x = cvt_pk_bf16(src[8 * s2], src[8 * s2 + 1]); w_.y = cvt_pk_bf16(src[8 * s2 + 2], src[8 * s2 + 3]); \
;             w_.z = cvt_pk_bf16(src[8 * s2 + 4], src[8 * s2 + 5]); w_.w = cvt_pk_bf16(src[8 * s2 + 6], src[8 * s2 + 7]); pf[kk][s2] = __builtin_bit_cast(bf16x8, w_); } } while (0)
; template <int MODE>
; __device__ __forceinline__ void att_smpv(f32x16 (&s)[2], f32x16 (&o)[4], float& mrun, float& lrun, float& Rrun, int tq, int tqmin, int tok0, int st, int dil, int h, int lane, const LAS unsigned char* vb) {
;     ...
;         f32x2 ps2 = (f32x2){0.f, 0.f};
; #pragma unroll
;         for (int kk = 0; kk < 2; ++kk)
; #pragma unroll
;             for (int e = 0; e < 16; e += 2) { const float p0 = __builtin_amdgcn_exp2f(s[kk][e] - mrun), p1 = __builtin_amdgcn_exp2f(s[kk][e + 1] - mrun); s[kk][e] = p0; s[kk][e + 1] = p1; ps2 += (f32x2){p0, p1}; }
;         lrun += ps2.x + ps2.y;
;         ATT_PACK(s[0], 0); ATT_PACK(s[1], 1);
;     ...
;     const int li = lane & 15, tq_ = li >> 2, tp = li & 3;
;     const unsigned base0 = (unsigned)((4 * h + tq_) * 256 + (tq_ << 6) + (2 * ((lane >> 4) & 1) + (tp >> 1)) * 16 + 8 * (tp & 1));
; #pragma unroll
;     for (int b = 0; b < 4; ++b)
; #pragma unroll
;         for (int kk = 0; kk < 2; ++kk)
; #pragma unroll
;             for (int s2 = 0; s2 < 2; ++s2) { const LAS unsigned char* p = vb + ((base0 ^ (unsigned)(b << 6)) + (unsigned)((32 * kk + 16 * s2) * 256));
;                 const s16x4 lo = vtr(p), hi = vtr(p + 8 * 256);
;                 const bf16x8 vf = (bf16x8){lo[0], lo[1], lo[2], lo[3], hi[0], hi[1], hi[2], hi[3]};
;                 o[b] = __builtin_amdgcn_mfma_f32_32x32x16_bf16(vf, pf[kk][s2], o[b], 0, 0, 0); }
.LBB0_309:
	v_sub_f32_e32 v248, v0, v177
	v_sub_f32_e32 v249, v83, v177
	v_sub_f32_e32 v250, v82, v177
	v_sub_f32_e32 v251, v85, v177
	v_exp_f32_e32 v80, v248
	v_exp_f32_e32 v81, v249
	v_exp_f32_e32 v82, v250
	v_exp_f32_e32 v83, v251
	v_sub_f32_e32 v248, v84, v177
	v_sub_f32_e32 v249, v87, v177
	v_sub_f32_e32 v250, v86, v177
	v_sub_f32_e32 v251, v89, v177
	v_exp_f32_e32 v84, v248
	v_exp_f32_e32 v85, v249
	v_exp_f32_e32 v86, v250
	v_exp_f32_e32 v87, v251
	v_sub_f32_e32 v248, v88, v177
	v_sub_f32_e32 v249, v91, v177
	v_sub_f32_e32 v250, v90, v177
	v_sub_f32_e32 v251, v93, v177
	v_exp_f32_e32 v88, v248
	v_exp_f32_e32 v89, v249
	v_exp_f32_e32 v90, v250
	v_exp_f32_e32 v91, v251
	v_sub_f32_e32 v248, v92, v177
	v_sub_f32_e32 v249, v95, v177
	v_sub_f32_e32 v250, v94, v177
	v_sub_f32_e32 v251, v96, v177
	v_exp_f32_e32 v92, v248
	v_exp_f32_e32 v93, v249
	v_exp_f32_e32 v94, v250
	v_exp_f32_e32 v95, v251
	v_sub_f32_e32 v248, v66, v177
	v_sub_f32_e32 v249, v97, v177
	v_exp_f32_e32 v96, v248
	v_exp_f32_e32 v97, v249
	v_sub_f32_e32 v0, v67, v177
	v_pk_add_f32 v[180:181], v[80:81], 0 op_sel_hi:[1,0]
	v_exp_f32_e32 v66, v0
	v_sub_f32_e32 v0, v178, v177
	v_pk_add_f32 v[180:181], v[82:83], v[180:181]
	v_exp_f32_e32 v67, v0
	v_sub_f32_e32 v0, v68, v177
	v_pk_add_f32 v[180:181], v[84:85], v[180:181]
	v_exp_f32_e32 v178, v0
	v_sub_f32_e32 v0, v179, v177
	v_pk_add_f32 v[180:181], v[86:87], v[180:181]
	v_exp_f32_e32 v179, v0
	v_sub_f32_e32 v0, v69, v177
	v_pk_add_f32 v[180:181], v[88:89], v[180:181]
	v_exp_f32_e32 v68, v0
	v_sub_f32_e32 v0, v73, v177
	v_pk_add_f32 v[180:181], v[90:91], v[180:181]
	v_exp_f32_e32 v69, v0
	v_sub_f32_e32 v0, v70, v177
	v_pk_add_f32 v[180:181], v[92:93], v[180:181]
	v_exp_f32_e32 v182, v0
	v_sub_f32_e32 v0, v75, v177
	v_pk_add_f32 v[180:181], v[94:95], v[180:181]
	v_exp_f32_e32 v183, v0
	v_sub_f32_e32 v0, v71, v177
	v_pk_add_f32 v[180:181], v[96:97], v[180:181]
	v_exp_f32_e32 v184, v0
	v_sub_f32_e32 v0, v76, v177
	v_pk_add_f32 v[180:181], v[66:67], v[180:181]
	v_exp_f32_e32 v185, v0
	v_pk_add_f32 v[180:181], v[178:179], v[180:181]
	v_sub_f32_e32 v0, v72, v177
	v_pk_add_f32 v[180:181], v[68:69], v[180:181]
	s_nop 0
	v_pk_add_f32 v[180:181], v[182:183], v[180:181]
	s_nop 0
	v_pk_add_f32 v[70:71], v[184:185], v[180:181]
	v_exp_f32_e32 v180, v0
	v_sub_f32_e32 v248, v77, v177
	v_sub_f32_e32 v249, v74, v177
	v_sub_f32_e32 v250, v78, v177
	v_exp_f32_e32 v181, v248
	v_exp_f32_e32 v186, v249
	v_exp_f32_e32 v187, v250
	v_pk_add_f32 v[70:71], v[180:181], v[70:71]
	s_nop 0
	v_pk_add_f32 v[70:71], v[186:187], v[70:71]
	s_nop 0
	v_add_f32_e32 v0, v70, v71
	v_add_f32_e32 v176, v176, v0
	v_add_u32_e32 v0, s48, v166
	v_cvt_pk_bf16_f32 v70, v80, v81
	v_cvt_pk_bf16_f32 v71, v82, v83
	v_cvt_pk_bf16_f32 v72, v84, v85
	v_cvt_pk_bf16_f32 v73, v86, v87
	v_cvt_pk_bf16_f32 v74, v88, v89
	v_cvt_pk_bf16_f32 v75, v90, v91
	v_cvt_pk_bf16_f32 v76, v92, v93
	v_cvt_pk_bf16_f32 v77, v94, v95
	v_cvt_pk_bf16_f32 v78, v96, v97
	v_cvt_pk_bf16_f32 v79, v66, v67
	v_cvt_pk_bf16_f32 v80, v178, v179
	v_cvt_pk_bf16_f32 v81, v68, v69
	v_cvt_pk_bf16_f32 v66, v182, v183
	v_cvt_pk_bf16_f32 v67, v184, v185
	v_cvt_pk_bf16_f32 v68, v180, v181
	v_cvt_pk_bf16_f32 v69, v186, v187
	s_waitcnt vmcnt(0)
	ds_read_b64_tr_b16 v[228:229], v0 offset:49152
	ds_read_b64_tr_b16 v[230:231], v0 offset:51200
	ds_read_b64_tr_b16 v[232:233], v0 offset:53248
	ds_read_b64_tr_b16 v[234:235], v0 offset:55296
	ds_read_b64_tr_b16 v[236:237], v0 offset:57344
	ds_read_b64_tr_b16 v[238:239], v0 offset:59392
	ds_read_b64_tr_b16 v[240:241], v0 offset:61440
	ds_read_b64_tr_b16 v[242:243], v0 offset:63488
	s_waitcnt lgkmcnt(6)
	v_mfma_f32_32x32x16_bf16 v[50:65], v[228:231], v[70:73], v[50:65]
	v_add_u32_e32 v0, s48, v167
	ds_read_b64_tr_b16 v[228:229], v0 offset:49152
	ds_read_b64_tr_b16 v[230:231], v0 offset:51200
	s_waitcnt lgkmcnt(6)
	v_mfma_f32_32x32x16_bf16 v[50:65], v[232:235], v[74:77], v[50:65]
	ds_read_b64_tr_b16 v[232:233], v0 offset:53248
	ds_read_b64_tr_b16 v[234:235], v0 offset:55296
	s_waitcnt lgkmcnt(6)
	v_mfma_f32_32x32x16_bf16 v[50:65], v[236:239], v[78:81], v[50:65]
	ds_read_b64_tr_b16 v[236:237], v0 offset:57344
	ds_read_b64_tr_b16 v[238:239], v0 offset:59392
	s_waitcnt lgkmcnt(6)
	v_mfma_f32_32x32x16_bf16 v[50:65], v[240:243], v[66:69], v[50:65]
	ds_read_b64_tr_b16 v[240:241], v0 offset:61440
	ds_read_b64_tr_b16 v[242:243], v0 offset:63488
	s_waitcnt lgkmcnt(6)
	v_mfma_f32_32x32x16_bf16 v[34:49], v[228:231], v[70:73], v[34:49]
	v_add_u32_e32 v0, s48, v168
	ds_read_b64_tr_b16 v[228:229], v0 offset:49152
	ds_read_b64_tr_b16 v[230:231], v0 offset:51200
	s_waitcnt lgkmcnt(6)
	v_mfma_f32_32x32x16_bf16 v[34:49], v[232:235], v[74:77], v[34:49]
	ds_read_b64_tr_b16 v[232:233], v0 offset:53248
	ds_read_b64_tr_b16 v[234:235], v0 offset:55296
	s_waitcnt lgkmcnt(6)
	v_mfma_f32_32x32x16_bf16 v[34:49], v[236:239], v[78:81], v[34:49]
	ds_read_b64_tr_b16 v[236:237], v0 offset:57344
	ds_read_b64_tr_b16 v[238:239], v0 offset:59392
	s_waitcnt lgkmcnt(6)
	v_mfma_f32_32x32x16_bf16 v[34:49], v[240:243], v[66:69], v[34:49]
	ds_read_b64_tr_b16 v[240:241], v0 offset:61440
	ds_read_b64_tr_b16 v[242:243], v0 offset:63488
	s_waitcnt lgkmcnt(6)
	v_mfma_f32_32x32x16_bf16 v[18:33], v[228:231], v[70:73], v[18:33]
	v_add_u32_e32 v0, s48, v169
	ds_read_b64_tr_b16 v[228:229], v0 offset:49152
	ds_read_b64_tr_b16 v[230:231], v0 offset:51200
	s_waitcnt lgkmcnt(6)
	v_mfma_f32_32x32x16_bf16 v[18:33], v[232:235], v[74:77], v[18:33]
	ds_read_b64_tr_b16 v[232:233], v0 offset:53248
	ds_read_b64_tr_b16 v[234:235], v0 offset:55296
	s_waitcnt lgkmcnt(6)
	v_mfma_f32_32x32x16_bf16 v[18:33], v[236:239], v[78:81], v[18:33]
	ds_read_b64_tr_b16 v[236:237], v0 offset:57344
	ds_read_b64_tr_b16 v[238:239], v0 offset:59392
	s_waitcnt lgkmcnt(6)
	v_mfma_f32_32x32x16_bf16 v[18:33], v[240:243], v[66:69], v[18:33]
	ds_read_b64_tr_b16 v[240:241], v0 offset:61440
	ds_read_b64_tr_b16 v[242:243], v0 offset:63488
	s_waitcnt lgkmcnt(6)
	v_mfma_f32_32x32x16_bf16 v[2:17], v[228:231], v[70:73], v[2:17]
	s_waitcnt lgkmcnt(4)
	v_mfma_f32_32x32x16_bf16 v[2:17], v[232:235], v[74:77], v[2:17]
	s_waitcnt lgkmcnt(2)
	v_mfma_f32_32x32x16_bf16 v[2:17], v[236:239], v[78:81], v[2:17]
	s_waitcnt lgkmcnt(0)
	v_mfma_f32_32x32x16_bf16 v[2:17], v[240:243], v[66:69], v[2:17]
